# same as the P2 prefetch/sink version with the metadata sgpr_count updated to match next_free_sgpr
# baseline (speedup 1.0000x reference)
; __global__ void __launch_bounds__(512, 2) mk_fwd(Args a) {
amdhsa.kernels:
  - .agpr_count:     0
    .args:
      - .offset:         0
        .size:           128
        .value_kind:     by_value
      - .offset:         128
        .size:           4
        .value_kind:     hidden_block_count_x
      - .offset:         132
        .size:           4
        .value_kind:     hidden_block_count_y
      - .offset:         136
        .size:           4
        .value_kind:     hidden_block_count_z
      - .offset:         140
        .size:           2
        .value_kind:     hidden_group_size_x
      - .offset:         142
        .size:           2
        .value_kind:     hidden_group_size_y
      - .offset:         144
        .size:           2
        .value_kind:     hidden_group_size_z
      - .offset:         146
        .size:           2
        .value_kind:     hidden_remainder_x
      - .offset:         148
        .size:           2
        .value_kind:     hidden_remainder_y
      - .offset:         150
        .size:           2
        .value_kind:     hidden_remainder_z
      - .offset:         168
        .size:           8
        .value_kind:     hidden_global_offset_x
      - .offset:         176
        .size:           8
        .value_kind:     hidden_global_offset_y
      - .offset:         184
        .size:           8
        .value_kind:     hidden_global_offset_z
      - .offset:         192
        .size:           2
        .value_kind:     hidden_grid_dims
      - .offset:         216
        .size:           8
        .value_kind:     hidden_multigrid_sync_arg
      - .offset:         248
        .size:           4
        .value_kind:     hidden_dynamic_lds_size
    .group_segment_fixed_size: 0
    .kernarg_segment_align: 8
    .kernarg_segment_size: 384
    .language:       OpenCL C
    .language_version:
      - 2
      - 0
    .max_flat_workgroup_size: 512
    .name:           _Z6mk_fwd4Args
    .private_segment_fixed_size: 0
    .sgpr_count:     108
    .sgpr_spill_count: 4
    .symbol:         _Z6mk_fwd4Args.kd
    .uniform_work_group_size: 1
    .uses_dynamic_stack: false
    .vgpr_count:     256
    .vgpr_spill_count: 0
    .wavefront_size: 64
